# stack: scan loads ahead + meta_gemm loops 8-deep + attention items ordered largest-first across heads
# baseline (speedup 1.0000x reference)
.LBB0_168:
.Lmg1_top:
	s_sub_i32 s100, s48, s22
	s_cmp_lt_i32 s100, 1
	s_cbranch_scc1 .Lmg1_done
	s_min_i32 s100, s100, 8
	s_sub_i32 s101, 8, s100
	s_lshl_b32 s1, s101, 5
	s_sub_i32 s26, s0, s1
	s_ashr_i32 s27, s26, 31
	s_lshl_b64 s[26:27], s[26:27], 1
	v_lshl_add_u64 v[212:213], v[10:11], 0, s[26:27]
	v_lshl_add_u64 v[228:229], v[12:13], 0, s[26:27]
	v_lshl_add_u64 v[238:239], v[14:15], 0, s[26:27]
	s_add_i32 s22, s22, s100
	s_lshl_b32 s1, s100, 5
	s_add_i32 s0, s0, s1
	s_cmp_eq_u32 s101, 0
	s_cbranch_scc1 .Lmg1_L0
	s_cmp_eq_u32 s101, 1
	s_cbranch_scc1 .Lmg1_L1
	s_cmp_eq_u32 s101, 2
	s_cbranch_scc1 .Lmg1_L2
	s_cmp_eq_u32 s101, 3
	s_cbranch_scc1 .Lmg1_L3
	s_cmp_eq_u32 s101, 4
	s_cbranch_scc1 .Lmg1_L4
	s_cmp_eq_u32 s101, 5
	s_cbranch_scc1 .Lmg1_L5
	s_cmp_eq_u32 s101, 6
	s_cbranch_scc1 .Lmg1_L6
	s_branch .Lmg1_L7
.Lmg1_L0:
	global_load_dwordx4 v[152:155], v[212:213], off
	global_load_dwordx4 v[156:159], v[228:229], off
	global_load_dwordx4 v[160:163], v[238:239], off
.Lmg1_L1:
	global_load_dwordx4 v[164:167], v[212:213], off offset:64
	global_load_dwordx4 v[168:171], v[228:229], off offset:64
	global_load_dwordx4 v[172:175], v[238:239], off offset:64
.Lmg1_L2:
	global_load_dwordx4 v[176:179], v[212:213], off offset:128
	global_load_dwordx4 v[180:183], v[228:229], off offset:128
	global_load_dwordx4 v[184:187], v[238:239], off offset:128
.Lmg1_L3:
	global_load_dwordx4 v[188:191], v[212:213], off offset:192
	global_load_dwordx4 v[192:195], v[228:229], off offset:192
	global_load_dwordx4 v[196:199], v[238:239], off offset:192
.Lmg1_L4:
	global_load_dwordx4 v[200:203], v[212:213], off offset:256
	global_load_dwordx4 v[204:207], v[228:229], off offset:256
	global_load_dwordx4 v[216:219], v[238:239], off offset:256
.Lmg1_L5:
	global_load_dwordx4 v[220:223], v[212:213], off offset:320
	global_load_dwordx4 v[224:227], v[228:229], off offset:320
	global_load_dwordx4 v[240:243], v[238:239], off offset:320
.Lmg1_L6:
	global_load_dwordx4 v[244:247], v[212:213], off offset:384
	global_load_dwordx4 v[248:251], v[228:229], off offset:384
	global_load_dwordx4 v[140:143], v[238:239], off offset:384
.Lmg1_L7:
	global_load_dwordx4 v[42:45], v[212:213], off offset:448
	global_load_dwordx4 v[46:49], v[228:229], off offset:448
	global_load_dwordx4 v[50:53], v[238:239], off offset:448
	s_cmp_eq_u32 s101, 0
	s_cbranch_scc1 .Lmg1_M0
	s_cmp_eq_u32 s101, 1
	s_cbranch_scc1 .Lmg1_M1
	s_cmp_eq_u32 s101, 2
	s_cbranch_scc1 .Lmg1_M2
	s_cmp_eq_u32 s101, 3
	s_cbranch_scc1 .Lmg1_M3
	s_cmp_eq_u32 s101, 4
	s_cbranch_scc1 .Lmg1_M4
	s_cmp_eq_u32 s101, 5
	s_cbranch_scc1 .Lmg1_M5
	s_cmp_eq_u32 s101, 6
	s_cbranch_scc1 .Lmg1_M6
	s_branch .Lmg1_M7
.Lmg1_M0:
	s_waitcnt vmcnt(21)
	v_mfma_f32_16x16x32_bf16 v[6:9], v[156:159], v[160:163], v[6:9]
	v_mfma_f32_16x16x32_bf16 v[2:5], v[152:155], v[160:163], v[2:5]
.Lmg1_M1:
	s_waitcnt vmcnt(18)
	v_mfma_f32_16x16x32_bf16 v[6:9], v[168:171], v[172:175], v[6:9]
	v_mfma_f32_16x16x32_bf16 v[2:5], v[164:167], v[172:175], v[2:5]
.Lmg1_M2:
	s_waitcnt vmcnt(15)
	v_mfma_f32_16x16x32_bf16 v[6:9], v[180:183], v[184:187], v[6:9]
	v_mfma_f32_16x16x32_bf16 v[2:5], v[176:179], v[184:187], v[2:5]
.Lmg1_M3:
	s_waitcnt vmcnt(12)
	v_mfma_f32_16x16x32_bf16 v[6:9], v[192:195], v[196:199], v[6:9]
	v_mfma_f32_16x16x32_bf16 v[2:5], v[188:191], v[196:199], v[2:5]
.Lmg1_M4:
	s_waitcnt vmcnt(9)
	v_mfma_f32_16x16x32_bf16 v[6:9], v[204:207], v[216:219], v[6:9]
	v_mfma_f32_16x16x32_bf16 v[2:5], v[200:203], v[216:219], v[2:5]
.Lmg1_M5:
	s_waitcnt vmcnt(6)
	v_mfma_f32_16x16x32_bf16 v[6:9], v[224:227], v[240:243], v[6:9]
	v_mfma_f32_16x16x32_bf16 v[2:5], v[220:223], v[240:243], v[2:5]
.Lmg1_M6:
	s_waitcnt vmcnt(3)
	v_mfma_f32_16x16x32_bf16 v[6:9], v[248:251], v[140:143], v[6:9]
	v_mfma_f32_16x16x32_bf16 v[2:5], v[244:247], v[140:143], v[2:5]
.Lmg1_M7:
	s_waitcnt vmcnt(0)
	v_mfma_f32_16x16x32_bf16 v[6:9], v[46:49], v[50:53], v[6:9]
	v_mfma_f32_16x16x32_bf16 v[2:5], v[42:45], v[50:53], v[2:5]
	s_branch .Lmg1_top
.Lmg1_done:
.LBB0_169:
	s_andn2_b64 vcc, exec, s[12:13]
	s_nop 5
	ds_write_b128 v62, v[2:5]
	ds_write_b128 v62, v[6:9] offset:1024
	s_waitcnt vmcnt(0) lgkmcnt(0)
	s_barrier
	s_cbranch_vccnz .LBB0_165
	ds_read_b128 v[2:5], v63
	ds_read_b128 v[6:9], v63 offset:1024
	ds_read_b128 v[10:13], v63 offset:2048
	s_ashr_i32 s0, s50, 3
	s_cmp_gt_i32 s0, 15
	s_waitcnt lgkmcnt(2)
	v_pk_add_f32 v[42:43], v[4:5], 0 op_sel_hi:[1,0]
	v_pk_add_f32 v[44:45], v[2:3], 0 op_sel_hi:[1,0]
	ds_read_b128 v[2:5], v63 offset:3072
	s_waitcnt lgkmcnt(2)
	v_pk_add_f32 v[46:47], v[8:9], 0 op_sel_hi:[1,0]
	v_pk_add_f32 v[48:49], v[6:7], 0 op_sel_hi:[1,0]
	s_waitcnt lgkmcnt(1)
	v_pk_add_f32 v[42:43], v[42:43], v[12:13]
	ds_read_b128 v[6:9], v63 offset:4096
	v_pk_add_f32 v[44:45], v[44:45], v[10:11]
	ds_read_b128 v[10:13], v63 offset:5120
	s_waitcnt lgkmcnt(2)
	v_pk_add_f32 v[46:47], v[46:47], v[4:5]
	v_pk_add_f32 v[48:49], v[48:49], v[2:3]
	ds_read_b128 v[2:5], v63 offset:6144
	s_waitcnt lgkmcnt(2)
	v_pk_add_f32 v[42:43], v[42:43], v[8:9]
	v_pk_add_f32 v[44:45], v[44:45], v[6:7]
	s_waitcnt lgkmcnt(1)
	v_pk_add_f32 v[46:47], v[46:47], v[12:13]
	ds_read_b128 v[6:9], v63 offset:7168
	v_pk_add_f32 v[48:49], v[48:49], v[10:11]
	ds_read_b128 v[10:13], v63 offset:8192
	s_waitcnt lgkmcnt(2)
	v_pk_add_f32 v[42:43], v[42:43], v[4:5]
	v_pk_add_f32 v[44:45], v[44:45], v[2:3]
	ds_read_b128 v[2:5], v63 offset:9216
	s_waitcnt lgkmcnt(2)
	v_pk_add_f32 v[46:47], v[46:47], v[8:9]
	v_pk_add_f32 v[48:49], v[48:49], v[6:7]
	s_waitcnt lgkmcnt(1)
	v_pk_add_f32 v[42:43], v[42:43], v[12:13]
	ds_read_b128 v[6:9], v63 offset:10240
	v_pk_add_f32 v[44:45], v[44:45], v[10:11]
	ds_read_b128 v[10:13], v63 offset:11264
	s_waitcnt lgkmcnt(2)
	v_pk_add_f32 v[46:47], v[46:47], v[4:5]
	v_pk_add_f32 v[48:49], v[48:49], v[2:3]
	ds_read_b128 v[2:5], v63 offset:12288
	s_waitcnt lgkmcnt(2)
	v_pk_add_f32 v[42:43], v[42:43], v[8:9]
	v_pk_add_f32 v[44:45], v[44:45], v[6:7]
	s_waitcnt lgkmcnt(1)
	v_pk_add_f32 v[46:47], v[46:47], v[12:13]
	v_pk_add_f32 v[48:49], v[48:49], v[10:11]
	ds_read_b128 v[6:9], v63 offset:13312
	ds_read_b128 v[10:13], v63 offset:14336
	s_waitcnt lgkmcnt(2)
	v_pk_add_f32 v[42:43], v[42:43], v[4:5]
	v_pk_add_f32 v[44:45], v[44:45], v[2:3]
	ds_read_b128 v[2:5], v63 offset:15360
	s_waitcnt lgkmcnt(2)
	v_pk_add_f32 v[6:7], v[48:49], v[6:7]
	s_waitcnt lgkmcnt(1)
	v_pk_add_f32 v[48:49], v[44:45], v[10:11]
	v_pk_add_f32 v[8:9], v[46:47], v[8:9]
	v_mul_f32_e32 v0, 0xbfb8aa3b, v48
	s_waitcnt lgkmcnt(0)
	v_pk_add_f32 v[44:45], v[6:7], v[2:3]
	v_exp_f32_e32 v0, v0
	v_mul_f32_e32 v2, 0xbfb8aa3b, v44
	v_exp_f32_e32 v3, v2
	v_pk_add_f32 v[46:47], v[42:43], v[12:13]
	v_add_f32_e32 v0, 1.0, v0
	v_rcp_f32_e32 v2, v0
	v_add_f32_e32 v0, 1.0, v3
	v_mul_f32_e32 v3, 0xbfb8aa3b, v49
	v_pk_add_f32 v[42:43], v[8:9], v[4:5]
	v_exp_f32_e32 v3, v3
	v_mul_f32_e32 v4, 0xbfb8aa3b, v45
	v_exp_f32_e32 v5, v4
	v_rcp_f32_e32 v4, v0
	v_add_f32_e32 v0, 1.0, v3
	v_rcp_f32_e32 v3, v0
	v_add_f32_e32 v0, 1.0, v5
	v_mul_f32_e32 v5, 0xbfb8aa3b, v46
	v_exp_f32_e32 v6, v5
	v_mul_f32_e32 v5, 0xbfb8aa3b, v42
	v_exp_f32_e32 v7, v5
	v_rcp_f32_e32 v5, v0
	v_add_f32_e32 v0, 1.0, v6
	v_mul_f32_e32 v6, 0xbfb8aa3b, v47
	v_rcp_f32_e32 v10, v0
	v_add_f32_e32 v0, 1.0, v7
	v_exp_f32_e32 v6, v6
	v_mul_f32_e32 v7, 0xbfb8aa3b, v43
	v_exp_f32_e32 v7, v7
	v_rcp_f32_e32 v12, v0
	v_add_f32_e32 v0, 1.0, v6
	v_rcp_f32_e32 v11, v0
	v_add_f32_e32 v0, 1.0, v7
	s_cselect_b64 s[36:37], -1, 0
	s_cmp_gt_u32 s0, 23
	v_rcp_f32_e32 v13, v0
	s_cselect_b64 s[40:41], -1, 0
	s_cmp_gt_u32 s0, 31
	s_cselect_b64 s[30:31], -1, 0
	s_cmp_gt_u32 s0, 39
	v_mov_b32_e32 v0, 0x78
	s_cselect_b64 s[22:23], -1, 0
	s_cmp_gt_u32 s0, 47
	v_bitop3_b32 v0, s44, v0, v60 bitop3:0xc8
	v_or_b32_e32 v52, s44, v60
	s_cselect_b64 s[26:27], -1, 0
	v_cvt_pk_bf16_f32 v6, v2, v3
	v_cvt_pk_bf16_f32 v8, v4, v5
	v_mov_b32_e32 v53, v1
	v_pk_mul_f32 v[2:3], v[48:49], v[2:3]
	v_pk_mul_f32 v[4:5], v[44:45], v[4:5]
	v_pk_mul_f32 v[50:51], v[46:47], v[10:11]
	v_pk_mul_f32 v[54:55], v[42:43], v[12:13]
	s_cmpk_gt_u32 s44, 0x1bff
	v_lshlrev_b32_e32 v0, 2, v0
	v_cvt_pk_bf16_f32 v7, v10, v11
	v_cvt_pk_bf16_f32 v9, v12, v13
	v_cvt_pk_bf16_f32 v10, v2, v3
	v_cvt_pk_bf16_f32 v11, v50, v51
	v_cvt_pk_bf16_f32 v12, v4, v5
	v_cvt_pk_bf16_f32 v13, v54, v55
	v_cvt_pk_bf16_f32 v2, v48, v49
	v_cvt_pk_bf16_f32 v3, v46, v47
	v_cvt_pk_bf16_f32 v4, v44, v45
	v_cvt_pk_bf16_f32 v5, v42, v43
	s_cselect_b64 s[0:1], -1, 0
	v_lshl_add_u64 v[50:51], v[52:53], 1, s[8:9]
	v_lshl_add_u64 v[54:55], s[42:43], 0, v[0:1]
	s_mov_b64 s[38:39], -1
	s_and_b64 vcc, exec, s[36:37]
	s_cbranch_vccz .LBB0_188
	s_and_b64 vcc, exec, s[40:41]
	s_cbranch_vccz .LBB0_185
	s_and_b64 vcc, exec, s[30:31]
	s_cbranch_vccz .LBB0_182
	v_lshl_add_u64 v[56:57], v[50:51], 0, v[18:19]
	s_and_b64 vcc, exec, s[22:23]
	s_cbranch_vccz .LBB0_179
	s_and_b64 vcc, exec, s[26:27]
	s_cbranch_vccz .LBB0_176
	global_store_dwordx4 v[56:57], v[6:9], off
	s_mov_b64 s[38:39], 0

.LBB0_365:
	v_readlane_b32 s0, v255, 23
	s_sub_i32 s6, s0, s8
	s_cmpk_gt_i32 s8, 0x87
	s_cselect_b64 s[0:1], -1, 0
	s_and_b64 s[12:13], s[0:1], exec
	s_cselect_b32 s30, s6, s7
	s_cmp_lt_i32 s30, 0
	s_mov_b64 s[6:7], -1
	s_cbranch_scc0 .LBB0_404
	s_and_b64 s[0:1], s[0:1], exec
	s_cselect_b32 s0, 0xffff, s8
	s_and_b32 s6, s0, 7
	s_lshr_b32 s12, s0, 3
	s_sub_i32 s0, 16, s12
	s_and_b32 s13, s0, 0xffff
	s_mov_b64 s[40:41], s[54:55]
	s_mov_b64 s[8:9], s[54:55]
	s_mov_b64 s[0:1], s[4:5]
	s_lshl_b32 s7, s6, 3
	v_mov_b32_e32 v177, v148
	global_load_dwordx2 v[160:161], v1, s[0:1] offset:72
	s_ashr_i32 s31, s6, 1
	s_and_b32 s0, s7, 8
	v_readlane_b32 s1, v254, 52
	s_or_b32 s14, s0, s1
	v_readfirstlane_b32 s61, v177
	s_ashr_i32 s65, s61, 8
	s_bfe_u32 s64, s61, 0x20006
	s_mul_i32 s6, s31, 0x4488000
	s_mul_hi_i32 s7, s31, 0x4488000
	s_add_u32 s0, s40, s6
	s_addc_u32 s1, s41, s7
	s_add_u32 s0, s0, 0x198a0200
	s_addc_u32 s1, s1, 0
	s_lshl_b32 s68, s13, 7
	s_lshl_b32 s69, s64, 5
	v_and_b32_e32 v182, 31, v177
	s_or_b32 s22, s69, s68
	v_or_b32_e32 v158, s22, v182
	v_mul_u32_u24_e32 v0, 0x4080, v158
	v_mov_b64_e32 v[2:3], s[0:1]
	v_lshl_add_u64 v[4:5], v[0:1], 1, s[0:1]
	s_lshl_b32 s60, s14, 7
	s_lshl_b32 s14, s14, 8
	s_lshl_b32 s0, s65, 6
	v_lshl_add_u64 v[4:5], v[4:5], 0, s[14:15]
	s_ashr_i32 s1, s0, 31
	v_bfe_u32 v22, v177, 5, 1
	v_lshl_add_u64 v[4:5], s[0:1], 1, v[4:5]
	s_and_b32 s0, s12, 0xffff
	s_lshl_b32 s66, s13, 1
	v_lshlrev_b32_e32 v0, 4, v22
	s_cmp_lg_u32 s0, 16
	v_lshl_add_u64 v[4:5], v[4:5], 0, v[0:1]
	s_cselect_b64 s[0:1], -1, 0
	v_ashrrev_i32_e32 v183, 4, v177
	global_load_dwordx4 v[112:115], v[4:5], off
	global_load_dwordx4 v[116:119], v[4:5], off offset:32
	global_load_dwordx4 v[120:123], v[4:5], off offset:64
	global_load_dwordx4 v[124:127], v[4:5], off offset:96
	v_mad_i64_i32 v[14:15], s[12:13], v183, s47, 0
	v_mad_i64_i32 v[2:3], s[12:13], v183, s47, v[2:3]
	v_lshlrev_b32_e32 v4, 4, v177
	s_and_b64 s[12:13], s[0:1], exec
	v_lshl_add_u64 v[2:3], v[2:3], 0, s[14:15]
	v_and_b32_e32 v20, 0xf0, v4
	v_mov_b32_e32 v21, v1
	s_cselect_b32 s12, 64, 0
	v_lshl_add_u64 v[2:3], v[2:3], 0, v[20:21]
	s_mul_i32 s14, s12, 0x8100
	v_lshl_add_u64 v[2:3], v[2:3], 0, s[14:15]
	s_movk_i32 s13, 0x2000
	v_add_co_u32_e32 v4, vcc, s13, v2
	s_mov_b32 s13, 0x104000
	s_nop 0
	v_addc_co_u32_e32 v5, vcc, 0, v3, vcc
	v_add_co_u32_e32 v2, vcc, s13, v2
	global_load_dwordx4 v[10:13], v[4:5], off offset:-4096
	global_load_dwordx4 v[16:19], v[4:5], off
	v_addc_co_u32_e32 v3, vcc, 0, v3, vcc
	global_load_dwordx4 v[6:9], v[2:3], off offset:-4096
	s_nop 0
	global_load_dwordx4 v[2:5], v[2:3], off
	v_cndmask_b32_e64 v21, 0, 1, s[0:1]
	v_add_u32_e32 v23, s12, v183
	s_movk_i32 s0, 0x70
	v_cmp_gt_i32_e32 vcc, s0, v23
	s_movk_i32 s0, 0x110
	v_mul_lo_u32 v180, v183, s0
	s_movk_i32 s0, 0x140
	v_mul_lo_u32 v181, v183, s0
	s_movk_i32 s0, 0x50
	v_lshlrev_b32_e32 v178, 2, v22
	s_add_i32 s14, s66, 2
	s_cmpk_lt_u32 s61, 0x100
	v_add_u32_e32 v179, 0, v20
	s_cselect_b64 s[26:27], -1, 0
	s_mov_b32 s22, 0x204000
	v_readfirstlane_b32 s67, v21
	s_mov_b64 s[12:13], -1
	v_cmp_lt_i32_e64 s[38:39], 15, v183
	v_mul_lo_u32 v164, v21, s22
	s_waitcnt vmcnt(3)
	v_cndmask_b32_e64 v131, v13, 0, vcc
	v_cndmask_b32_e64 v130, v12, 0, vcc
	v_cndmask_b32_e64 v129, v11, 0, vcc
	v_cndmask_b32_e64 v128, v10, 0, vcc
	s_waitcnt vmcnt(2)
	v_cndmask_b32_e64 v135, v19, 0, vcc
	v_cndmask_b32_e64 v134, v18, 0, vcc
	v_cndmask_b32_e64 v133, v17, 0, vcc
	v_cndmask_b32_e64 v132, v16, 0, vcc
	v_cmp_gt_i32_e32 vcc, s0, v23
	v_add_u32_e32 v10, v179, v180
	v_add_u32_e32 v11, v179, v181
	s_waitcnt vmcnt(0)
	v_cndmask_b32_e64 v140, v2, 0, vcc
	v_lshrrev_b32_e32 v2, 2, v177
	v_cndmask_b32_e64 v142, v4, 0, vcc
	v_cndmask_b32_e64 v141, v3, 0, vcc
	v_and_or_b32 v2, v2, 3, v178
	v_and_b32_e32 v3, 16, v177
	v_lshlrev_b32_e32 v4, 2, v177
	v_mul_u32_u24_e32 v2, 0x140, v2
	v_and_or_b32 v3, v4, 12, v3
	v_lshl_or_b32 v184, v3, 1, v2
	v_sub_u32_e32 v2, v178, v182
	v_and_b32_e32 v3, 15, v177
	v_cndmask_b32_e64 v139, v9, 0, vcc
	v_cndmask_b32_e64 v138, v8, 0, vcc
	v_cndmask_b32_e64 v137, v7, 0, vcc
	v_cndmask_b32_e64 v136, v6, 0, vcc
	v_cndmask_b32_e64 v143, v5, 0, vcc
	s_and_b64 vcc, exec, s[26:27]
	v_cmp_lt_i32_e64 s[0:1], 47, v183
	v_subrev_u32_e32 v185, s69, v2
	v_lshlrev_b32_e32 v162, 4, v3
	ds_write_b128 v10, v[128:131]
	ds_write_b128 v11, v[132:135] offset:34816
	ds_write_b128 v10, v[136:139] offset:8704
	ds_write_b128 v11, v[140:143] offset:45056
	s_waitcnt lgkmcnt(0)
	s_barrier
	s_cbranch_vccnz .LBB0_384
	s_cmp_lg_u32 0, -1
	s_cselect_b32 s12, 0, 0
	s_add_i32 s12, s12, 0x8800
	v_add_u32_e32 v186, s12, v184
	s_movk_i32 s12, 0x110
	v_mad_u32_u24 v2, v182, s12, 0
	s_lshl_b32 s12, s65, 7
	v_add3_u32 v187, v2, v0, s12
	s_lshl_b32 s78, s67, 6
	v_subrev_u32_e32 v2, s68, v185
	v_add_u32_e32 v2, s78, v2
	s_add_i32 s12, s68, s69
	v_add_u32_e32 v189, 59, v2
	v_add_u32_e32 v190, 32, v2
	v_add_u32_e32 v191, 11, v2
	v_add_u32_e32 v192, 10, v2
	v_add_u32_e32 v193, 9, v2
	v_add_u32_e32 v194, 8, v2
	v_add_u32_e32 v195, 3, v2
	v_add_u32_e32 v196, 2, v2
	v_add_u32_e32 v197, 1, v2
	v_add_u32_e32 v2, s12, v182
	v_sub_u32_e32 v2, v2, v178
	v_mov_b32_e32 v165, v1
	v_subrev_u32_e32 v198, s78, v2
	v_lshl_add_u64 v[2:3], s[6:7], 0, v[164:165]
	s_lshl_b32 s12, s60, 1
	v_lshl_add_u64 v[2:3], v[2:3], 0, v[14:15]
	v_mov_b32_e32 v163, v1
	s_add_u32 s12, s40, s12
	v_lshl_add_u64 v[2:3], v[2:3], 0, v[162:163]
	s_addc_u32 s13, s41, 0
	v_lshl_add_u64 v[2:3], s[12:13], 0, v[2:3]
	s_mov_b64 s[12:13], 0x19ba8200
	v_mov_b32_e32 v30, v1
	v_mov_b32_e32 v31, v1
	v_lshl_add_u64 v[166:167], v[2:3], 0, s[12:13]
	v_mov_b32_e32 v16, v1
	v_mov_b32_e32 v17, v1
	v_mov_b32_e32 v18, v1
	v_mov_b32_e32 v19, v1
	v_mov_b32_e32 v20, v1
	v_mov_b32_e32 v21, v1
	v_mov_b32_e32 v22, v1
	v_mov_b32_e32 v23, v1
	v_mov_b32_e32 v24, v1
	v_mov_b32_e32 v25, v1
	v_mov_b32_e32 v26, v1
	v_mov_b32_e32 v27, v1
	v_mov_b32_e32 v28, v1
	v_mov_b32_e32 v29, v1
	v_mov_b64_e32 v[46:47], v[30:31]
	v_mov_b64_e32 v[62:63], v[30:31]
	v_mov_b64_e32 v[78:79], v[30:31]
	v_mov_b64_e32 v[6:7], v[136:137]
	v_mov_b64_e32 v[2:3], v[128:129]
	v_mov_b64_e32 v[146:147], v[142:143]
	v_mov_b64_e32 v[10:11], v[132:133]
	s_mov_b32 s77, 0
	v_mov_b32_e32 v149, v158
	v_or_b32_e32 v188, s78, v178
	s_mov_b32 s23, 2
	v_mov_b32_e32 v163, 0
	v_mov_b32_e32 v165, 0xff800000
	v_mov_b64_e32 v[44:45], v[28:29]
	v_mov_b64_e32 v[42:43], v[26:27]
	v_mov_b64_e32 v[40:41], v[24:25]
	v_mov_b64_e32 v[38:39], v[22:23]
	v_mov_b64_e32 v[36:37], v[20:21]
	v_mov_b64_e32 v[34:35], v[18:19]
	v_mov_b64_e32 v[32:33], v[16:17]
	v_mov_b64_e32 v[60:61], v[28:29]
	v_mov_b64_e32 v[58:59], v[26:27]
	v_mov_b64_e32 v[56:57], v[24:25]
	v_mov_b64_e32 v[54:55], v[22:23]
	v_mov_b64_e32 v[52:53], v[20:21]
	v_mov_b64_e32 v[50:51], v[18:19]
	v_mov_b64_e32 v[48:49], v[16:17]
	v_mov_b64_e32 v[76:77], v[28:29]
	v_mov_b64_e32 v[74:75], v[26:27]
	v_mov_b64_e32 v[72:73], v[24:25]
	v_mov_b64_e32 v[70:71], v[22:23]
	v_mov_b64_e32 v[68:69], v[20:21]
	v_mov_b64_e32 v[66:67], v[18:19]
	v_mov_b64_e32 v[64:65], v[16:17]
	v_mov_b64_e32 v[8:9], v[138:139]
	v_mov_b64_e32 v[4:5], v[130:131]
	v_mov_b64_e32 v[144:145], v[140:141]
	v_mov_b64_e32 v[12:13], v[134:135]
	s_mov_b32 s79, 0
	s_mov_b32 s42, 0
	s_mov_b32 s22, s67

.LBB0_736:
.Lmg2_top:
	s_sub_i32 s100, s8, s9
	s_cmp_lt_i32 s100, 1
	s_cbranch_scc1 .Lmg2_done
	s_min_i32 s100, s100, 8
	s_sub_i32 s101, 8, s100
	s_lshl_b32 s1, s101, 5
	s_sub_i32 s12, s0, s1
	s_ashr_i32 s13, s12, 31
	s_lshl_b64 s[12:13], s[12:13], 1
	v_lshl_add_u64 v[212:213], v[10:11], 0, s[12:13]
	v_lshl_add_u64 v[228:229], v[12:13], 0, s[12:13]
	v_lshl_add_u64 v[238:239], v[14:15], 0, s[12:13]
	s_add_i32 s9, s9, s100
	s_lshl_b32 s1, s100, 5
	s_add_i32 s0, s0, s1
	s_cmp_eq_u32 s101, 0
	s_cbranch_scc1 .Lmg2_L0
	s_cmp_eq_u32 s101, 1
	s_cbranch_scc1 .Lmg2_L1
	s_cmp_eq_u32 s101, 2
	s_cbranch_scc1 .Lmg2_L2
	s_cmp_eq_u32 s101, 3
	s_cbranch_scc1 .Lmg2_L3
	s_cmp_eq_u32 s101, 4
	s_cbranch_scc1 .Lmg2_L4
	s_cmp_eq_u32 s101, 5
	s_cbranch_scc1 .Lmg2_L5
	s_cmp_eq_u32 s101, 6
	s_cbranch_scc1 .Lmg2_L6
	s_branch .Lmg2_L7

.Lmg2_L7:
	global_load_dwordx4 v[24:27], v[212:213], off offset:448
	global_load_dwordx4 v[30:33], v[228:229], off offset:448
	global_load_dwordx4 v[20:23], v[238:239], off offset:448
	s_cmp_eq_u32 s101, 0
	s_cbranch_scc1 .Lmg2_M0
	s_cmp_eq_u32 s101, 1
	s_cbranch_scc1 .Lmg2_M1
	s_cmp_eq_u32 s101, 2
	s_cbranch_scc1 .Lmg2_M2
	s_cmp_eq_u32 s101, 3
	s_cbranch_scc1 .Lmg2_M3
	s_cmp_eq_u32 s101, 4
	s_cbranch_scc1 .Lmg2_M4
	s_cmp_eq_u32 s101, 5
	s_cbranch_scc1 .Lmg2_M5
	s_cmp_eq_u32 s101, 6
	s_cbranch_scc1 .Lmg2_M6
	s_branch .Lmg2_M7

.Lmg2_M7:
	s_waitcnt vmcnt(0)
	v_mfma_f32_16x16x32_bf16 v[6:9], v[30:33], v[20:23], v[6:9]
	v_mfma_f32_16x16x32_bf16 v[2:5], v[24:27], v[20:23], v[2:5]
	s_branch .Lmg2_top
.Lmg2_done:
.LBB0_737:
	v_lshlrev_b32_e32 v0, 2, v16
	s_lshl_b32 s0, s7, 11
	v_and_b32_e32 v0, 0xfc, v0
	s_add_i32 s0, s0, 0
	v_lshl_add_u32 v10, v0, 2, s0
	s_cmp_gt_u32 s6, 63
	ds_write_b128 v10, v[2:5]
	ds_write_b128 v10, v[6:9] offset:1024
	s_waitcnt lgkmcnt(0)
	s_barrier
	s_cbranch_scc1 .LBB0_739
	v_lshl_add_u32 v0, v0, 2, 0
	ds_read_b128 v[14:17], v0
	ds_read_b128 v[20:23], v0 offset:1024
	ds_read_b128 v[24:27], v0 offset:2048
	ds_read_b128 v[30:33], v0 offset:3072
	ds_read_b128 v[34:37], v0 offset:4096
	ds_read_b128 v[38:41], v0 offset:5120
	ds_read_b128 v[42:45], v0 offset:6144
	ds_read_b128 v[46:49], v0 offset:7168
	ds_read_b128 v[2:5], v0 offset:8192
	v_readlane_b32 s0, v254, 37
	s_waitcnt lgkmcnt(0)
	v_pk_add_f32 v[6:7], v[4:5], 0 op_sel_hi:[1,0]
	v_pk_add_f32 v[8:9], v[2:3], 0 op_sel_hi:[1,0]
	ds_read_b128 v[2:5], v0 offset:9216
	s_waitcnt lgkmcnt(0)
	v_pk_add_f32 v[10:11], v[4:5], 0 op_sel_hi:[1,0]
	v_pk_add_f32 v[12:13], v[2:3], 0 op_sel_hi:[1,0]
	ds_read_b128 v[2:5], v0 offset:10240
	s_waitcnt lgkmcnt(0)
	v_pk_add_f32 v[6:7], v[6:7], v[4:5]
	v_pk_add_f32 v[8:9], v[8:9], v[2:3]
	ds_read_b128 v[2:5], v0 offset:11264
	s_waitcnt lgkmcnt(0)
	v_pk_add_f32 v[10:11], v[10:11], v[4:5]
	v_pk_add_f32 v[12:13], v[12:13], v[2:3]
	ds_read_b128 v[2:5], v0 offset:12288
	s_waitcnt lgkmcnt(0)
	v_pk_add_f32 v[6:7], v[6:7], v[4:5]
	v_pk_add_f32 v[8:9], v[8:9], v[2:3]
	ds_read_b128 v[2:5], v0 offset:13312
	s_waitcnt lgkmcnt(0)
	v_pk_add_f32 v[50:51], v[10:11], v[4:5]
	v_pk_add_f32 v[52:53], v[12:13], v[2:3]
	ds_read_b128 v[2:5], v0 offset:14336
	s_waitcnt lgkmcnt(0)
	v_pk_add_f32 v[10:11], v[6:7], v[4:5]
	ds_read_b128 v[4:7], v0 offset:15360
	v_pk_add_f32 v[12:13], v[8:9], v[2:3]
	v_pk_add_f32 v[8:9], v[14:15], 0 op_sel_hi:[1,0]
	v_pk_add_f32 v[14:15], v[22:23], 0 op_sel_hi:[1,0]
	v_pk_add_f32 v[8:9], v[8:9], v[24:25]
	s_waitcnt lgkmcnt(0)
	v_pk_add_f32 v[2:3], v[50:51], v[6:7]
	v_pk_add_f32 v[6:7], v[52:53], v[4:5]
	v_pk_add_f32 v[4:5], v[16:17], 0 op_sel_hi:[1,0]
	v_pk_add_f32 v[16:17], v[20:21], 0 op_sel_hi:[1,0]
	v_pk_add_f32 v[14:15], v[14:15], v[32:33]
	v_pk_add_f32 v[4:5], v[4:5], v[26:27]
	v_pk_add_f32 v[16:17], v[16:17], v[30:31]
	v_pk_add_f32 v[8:9], v[8:9], v[34:35]
	v_pk_add_f32 v[20:21], v[14:15], v[40:41]
	v_pk_add_f32 v[4:5], v[4:5], v[36:37]
	v_pk_add_f32 v[22:23], v[16:17], v[38:39]
	v_pk_add_f32 v[16:17], v[8:9], v[42:43]
	v_pk_add_f32 v[8:9], v[20:21], v[48:49]
	v_or_b32_e32 v20, s0, v19
	v_pk_add_f32 v[14:15], v[4:5], v[44:45]
	v_pk_add_f32 v[4:5], v[22:23], v[46:47]
	v_mov_b64_e32 v[22:23], s[38:39]
	v_ashrrev_i32_e32 v21, 31, v20
	v_mad_u64_u32 v[22:23], s[0:1], v18, s47, v[22:23]
	v_lshlrev_b64 v[18:19], 1, v[20:21]
	v_lshl_add_u64 v[20:21], v[22:23], 0, v[18:19]
	v_add_co_u32_e32 v30, vcc, s72, v20
	v_lshlrev_b32_e32 v0, 12, v28
	s_nop 0
	v_addc_co_u32_e32 v31, vcc, 0, v21, vcc
	global_load_dwordx4 v[20:23], v[30:31], off offset:-4096
	s_mov_b32 s0, 0x70000
	global_load_dwordx4 v[30:33], v[30:31], off
	s_waitcnt vmcnt(1)
	v_lshlrev_b32_e32 v24, 16, v20
	v_and_b32_e32 v25, 0xffff0000, v20
	s_waitcnt vmcnt(0)
	v_lshlrev_b32_e32 v36, 16, v32
	v_and_b32_e32 v37, 0xffff0000, v32
	v_lshlrev_b32_e32 v26, 16, v21
	v_and_b32_e32 v27, 0xffff0000, v21
	v_lshlrev_b32_e32 v20, 16, v22
	v_and_b32_e32 v21, 0xffff0000, v22
	v_lshlrev_b32_e32 v32, 16, v33
	v_and_b32_e32 v33, 0xffff0000, v33
	v_pk_mul_f32 v[6:7], v[6:7], v[36:37]
	v_lshlrev_b32_e32 v22, 16, v23
	v_and_b32_e32 v23, 0xffff0000, v23
	v_lshlrev_b32_e32 v34, 16, v30
	v_and_b32_e32 v35, 0xffff0000, v30
	v_lshlrev_b32_e32 v30, 16, v31
	v_and_b32_e32 v31, 0xffff0000, v31
	v_pk_mul_f32 v[2:3], v[2:3], v[32:33]
	v_pk_fma_f32 v[4:5], v[4:5], v[20:21], v[6:7]
	v_lshl_add_u64 v[6:7], s[28:29], 0, v[0:1]
	v_pk_mul_f32 v[12:13], v[12:13], v[34:35]
	v_pk_mul_f32 v[10:11], v[10:11], v[30:31]
	v_pk_fma_f32 v[8:9], v[8:9], v[22:23], v[2:3]
	v_lshl_add_u64 v[6:7], v[6:7], 0, v[18:19]
	v_pk_fma_f32 v[10:11], v[14:15], v[26:27], v[10:11]
	v_pk_fma_f32 v[12:13], v[16:17], v[24:25], v[12:13]
	v_cvt_pk_bf16_f32 v4, v4, v5
	v_cvt_pk_bf16_f32 v5, v8, v9
	v_add_co_u32_e32 v8, vcc, s0, v6
	v_cvt_pk_bf16_f32 v2, v12, v13
	v_cvt_pk_bf16_f32 v3, v10, v11
	v_addc_co_u32_e32 v9, vcc, 0, v7, vcc
	global_store_dwordx4 v[8:9], v[2:5], off
	v_add_co_u32_e32 v8, vcc, 0x8f0000, v6
	s_nop 1
	v_addc_co_u32_e32 v9, vcc, 0, v7, vcc
	global_store_dwordx4 v[8:9], v[2:5], off
	v_add_co_u32_e32 v8, vcc, 0x1170000, v6
	s_nop 1
	v_addc_co_u32_e32 v9, vcc, 0, v7, vcc
	v_add_co_u32_e32 v6, vcc, 0x19f0000, v6
	global_store_dwordx4 v[8:9], v[2:5], off
	s_nop 0
	v_addc_co_u32_e32 v7, vcc, 0, v7, vcc
	global_store_dwordx4 v[6:7], v[2:5], off

.LBB0_853:
.Lmg3_top:
	s_sub_i32 s100, s7, s8
	s_cmp_lt_i32 s100, 1
	s_cbranch_scc1 .Lmg3_done
	s_min_i32 s100, s100, 8
	s_sub_i32 s101, 8, s100
	s_lshl_b32 s1, s101, 5
	s_sub_i32 s12, s0, s1
	s_ashr_i32 s13, s12, 31
	s_lshl_b64 s[12:13], s[12:13], 1
	v_lshl_add_u64 v[212:213], v[10:11], 0, s[12:13]
	v_lshl_add_u64 v[228:229], v[12:13], 0, s[12:13]
	v_lshl_add_u64 v[238:239], v[14:15], 0, s[12:13]
	s_add_i32 s8, s8, s100
	s_lshl_b32 s1, s100, 5
	s_add_i32 s0, s0, s1
	s_cmp_eq_u32 s101, 0
	s_cbranch_scc1 .Lmg3_L0
	s_cmp_eq_u32 s101, 1
	s_cbranch_scc1 .Lmg3_L1
	s_cmp_eq_u32 s101, 2
	s_cbranch_scc1 .Lmg3_L2
	s_cmp_eq_u32 s101, 3
	s_cbranch_scc1 .Lmg3_L3
	s_cmp_eq_u32 s101, 4
	s_cbranch_scc1 .Lmg3_L4
	s_cmp_eq_u32 s101, 5
	s_cbranch_scc1 .Lmg3_L5
	s_cmp_eq_u32 s101, 6
	s_cbranch_scc1 .Lmg3_L6
	s_branch .Lmg3_L7

.Lmg3_L7:
	global_load_dwordx4 v[22:25], v[212:213], off offset:448
	global_load_dwordx4 v[26:29], v[228:229], off offset:448
	global_load_dwordx4 v[30:33], v[238:239], off offset:448
	s_cmp_eq_u32 s101, 0
	s_cbranch_scc1 .Lmg3_M0
	s_cmp_eq_u32 s101, 1
	s_cbranch_scc1 .Lmg3_M1
	s_cmp_eq_u32 s101, 2
	s_cbranch_scc1 .Lmg3_M2
	s_cmp_eq_u32 s101, 3
	s_cbranch_scc1 .Lmg3_M3
	s_cmp_eq_u32 s101, 4
	s_cbranch_scc1 .Lmg3_M4
	s_cmp_eq_u32 s101, 5
	s_cbranch_scc1 .Lmg3_M5
	s_cmp_eq_u32 s101, 6
	s_cbranch_scc1 .Lmg3_M6
	s_branch .Lmg3_M7

.Lmg3_M7:
	s_waitcnt vmcnt(0)
	v_mfma_f32_16x16x32_bf16 v[6:9], v[26:29], v[30:33], v[6:9]
	v_mfma_f32_16x16x32_bf16 v[2:5], v[22:25], v[30:33], v[2:5]
	s_branch .Lmg3_top
.Lmg3_done:
.LBB0_854:
	s_lshl_b32 s0, s6, 5
	s_and_b32 s0, s0, 0xfffff800
	v_and_b32_e32 v20, 63, v20
	s_add_i32 s0, s0, 0
	v_lshl_add_u32 v0, v20, 4, s0
	s_cmp_gt_u32 s6, 63
	s_nop 0
	ds_write_b128 v0, v[2:5]
	ds_write_b128 v0, v[6:9] offset:1024
	s_waitcnt lgkmcnt(0)
	s_barrier
	s_cbranch_scc1 .LBB0_877
	v_lshlrev_b32_e32 v0, 2, v20
	v_lshl_add_u32 v0, v0, 2, 0
	ds_read_b128 v[2:5], v0
	v_readlane_b32 s0, v254, 37
	s_movk_i32 s70, 0x80
	v_cmp_gt_u32_e32 vcc, 16, v20
	s_waitcnt lgkmcnt(0)
	v_pk_add_f32 v[6:7], v[4:5], 0 op_sel_hi:[1,0]
	v_pk_add_f32 v[8:9], v[2:3], 0 op_sel_hi:[1,0]
	ds_read_b128 v[2:5], v0 offset:1024
	s_waitcnt lgkmcnt(0)
	v_pk_add_f32 v[10:11], v[4:5], 0 op_sel_hi:[1,0]
	v_pk_add_f32 v[12:13], v[2:3], 0 op_sel_hi:[1,0]
	ds_read_b128 v[2:5], v0 offset:2048
	s_waitcnt lgkmcnt(0)
	v_pk_add_f32 v[6:7], v[6:7], v[4:5]
	v_pk_add_f32 v[8:9], v[8:9], v[2:3]
	ds_read_b128 v[2:5], v0 offset:3072
	s_waitcnt lgkmcnt(0)
	v_pk_add_f32 v[10:11], v[10:11], v[4:5]
	v_pk_add_f32 v[12:13], v[12:13], v[2:3]
	ds_read_b128 v[2:5], v0 offset:4096
	s_waitcnt lgkmcnt(0)
	v_pk_add_f32 v[6:7], v[6:7], v[4:5]
	v_pk_add_f32 v[8:9], v[8:9], v[2:3]
	ds_read_b128 v[2:5], v0 offset:5120
	s_waitcnt lgkmcnt(0)
	v_pk_add_f32 v[10:11], v[10:11], v[4:5]
	v_pk_add_f32 v[12:13], v[12:13], v[2:3]
	ds_read_b128 v[2:5], v0 offset:6144
	s_waitcnt lgkmcnt(0)
	v_pk_add_f32 v[6:7], v[6:7], v[4:5]
	v_pk_add_f32 v[8:9], v[8:9], v[2:3]
	ds_read_b128 v[2:5], v0 offset:7168
	s_waitcnt lgkmcnt(0)
	v_pk_add_f32 v[10:11], v[10:11], v[4:5]
	v_pk_add_f32 v[12:13], v[12:13], v[2:3]
	ds_read_b128 v[2:5], v0 offset:8192
	s_waitcnt lgkmcnt(0)
	v_pk_add_f32 v[6:7], v[6:7], v[4:5]
	v_pk_add_f32 v[8:9], v[8:9], v[2:3]
	ds_read_b128 v[2:5], v0 offset:9216
	s_waitcnt lgkmcnt(0)
	v_pk_add_f32 v[10:11], v[10:11], v[4:5]
	v_pk_add_f32 v[12:13], v[12:13], v[2:3]
	ds_read_b128 v[2:5], v0 offset:10240
	s_waitcnt lgkmcnt(0)
	v_pk_add_f32 v[6:7], v[6:7], v[4:5]
	v_pk_add_f32 v[8:9], v[8:9], v[2:3]
	ds_read_b128 v[2:5], v0 offset:11264
	s_waitcnt lgkmcnt(0)
	v_pk_add_f32 v[10:11], v[10:11], v[4:5]
	v_pk_add_f32 v[12:13], v[12:13], v[2:3]
	ds_read_b128 v[2:5], v0 offset:12288
	s_waitcnt lgkmcnt(0)
	v_pk_add_f32 v[14:15], v[6:7], v[4:5]
	v_pk_add_f32 v[8:9], v[8:9], v[2:3]
	ds_read_b128 v[2:5], v0 offset:13312
	s_waitcnt lgkmcnt(0)
	v_pk_add_f32 v[10:11], v[10:11], v[4:5]
	ds_read_b128 v[4:7], v0 offset:14336
	v_pk_add_f32 v[22:23], v[12:13], v[2:3]
	s_waitcnt lgkmcnt(0)
	v_pk_add_f32 v[2:3], v[14:15], v[6:7]
	v_pk_add_f32 v[4:5], v[8:9], v[4:5]
	ds_read_b128 v[6:9], v0 offset:15360
	v_or_b32_e32 v14, s0, v17
	v_lshlrev_b32_e32 v0, 13, v16
	v_ashrrev_i32_e32 v15, 31, v14
	s_mov_b32 s0, 0x3fb504f3
	s_waitcnt lgkmcnt(0)
	v_pk_add_f32 v[12:13], v[10:11], v[8:9]
	v_pk_add_f32 v[10:11], v[22:23], v[6:7]
	v_lshl_add_u64 v[6:7], s[28:29], 0, v[0:1]
	v_lshl_add_u64 v[16:17], v[14:15], 2, v[6:7]
	global_load_dwordx4 v[22:25], v[16:17], off offset:16
	global_load_dwordx4 v[6:9], v[16:17], off
	s_waitcnt vmcnt(0)
	v_pk_fma_f32 v[8:9], v[8:9], s[0:1], v[2:3] op_sel_hi:[1,0,1]
	v_pk_fma_f32 v[6:7], v[6:7], s[0:1], v[4:5] op_sel_hi:[1,0,1]
	v_pk_fma_f32 v[2:3], v[24:25], s[0:1], v[12:13] op_sel_hi:[1,0,1]
	v_pk_fma_f32 v[4:5], v[22:23], s[0:1], v[10:11] op_sel_hi:[1,0,1]
	v_pk_mov_b32 v[10:11], v[6:7], v[8:9] op_sel:[1,0]
	v_mov_b32_e32 v12, v6
	v_mov_b32_e32 v13, v9
	v_pk_add_f32 v[10:11], v[10:11], v[12:13]
	v_pk_mul_f32 v[12:13], v[8:9], v[8:9]
	v_pk_mul_f32 v[22:23], v[6:7], v[6:7]
	v_mul_f32_e32 v0, v4, v4
	v_pk_mov_b32 v[24:25], v[22:23], v[12:13] op_sel:[1,0]
	v_mov_b32_e32 v23, v13
	v_pk_add_f32 v[12:13], v[24:25], v[22:23]
	v_pk_fma_f32 v[22:23], v[4:5], v[4:5], v[0:1] op_sel_hi:[1,1,0]
	v_pk_add_f32 v[12:13], v[12:13], v[12:13] op_sel_hi:[0,1]
	v_mov_b32_e32 v12, v148
	v_mov_b32_e32 v22, v3
	v_lshlrev_b32_e32 v12, 2, v12
	v_bitop3_b32 v21, v12, 64, v232 bitop3:0x6c
	v_mov_b32_e32 v12, v148
	v_mul_f32_e32 v0, v2, v2
	v_lshlrev_b32_e32 v12, 2, v12
	v_bitop3_b32 v26, v12, 64, v232 bitop3:0x6c
	v_mov_b32_e32 v12, v2
	v_pk_add_f32 v[12:13], v[12:13], v[22:23]
	v_pk_add_f32 v[22:23], v[4:5], v[4:5] op_sel:[0,1] op_sel_hi:[1,0]
	v_pk_mul_f32 v[24:25], v[2:3], v[2:3]
	v_pk_add_f32 v[10:11], v[10:11], v[10:11] op_sel:[0,1] op_sel_hi:[1,0]
	v_mov_b32_e32 v23, v25
	v_mov_b32_e32 v11, v0
	v_pk_add_f32 v[10:11], v[10:11], v[22:23]
	v_mov_b32_e32 v0, v148
	v_pk_add_f32 v[10:11], v[10:11], v[12:13]
	ds_bpermute_b32 v12, v21, v10
	ds_bpermute_b32 v13, v26, v11
	s_movk_i32 s0, 0x80
	v_lshlrev_b32_e32 v0, 2, v0
	v_bitop3_b32 v0, v0, s0, v232 bitop3:0x6c
	s_waitcnt lgkmcnt(0)
	v_pk_add_f32 v[10:11], v[10:11], v[12:13]
	ds_bpermute_b32 v12, v0, v10
	v_mov_b32_e32 v0, v148
	s_nop 0
	v_lshlrev_b32_e32 v0, 2, v0
	v_bitop3_b32 v0, v0, s0, v232 bitop3:0x6c
	ds_bpermute_b32 v13, v0, v11
	s_and_saveexec_b64 s[0:1], vcc
	s_cbranch_execz .LBB0_857
	v_readlane_b32 s6, v254, 37
	s_waitcnt lgkmcnt(0)
	v_pk_add_f32 v[10:11], v[10:11], v[12:13]
	v_or_b32_e32 v12, s6, v19
	v_readlane_b32 s6, v254, 42
	v_ashrrev_i32_e32 v13, 31, v12
	v_readlane_b32 s7, v254, 43
	s_nop 1
	v_lshl_add_u64 v[12:13], v[12:13], 2, s[6:7]
	global_store_dwordx2 v[12:13], v[10:11], off sc1

.LBB0_949:
.Lmg4_top:
	s_sub_i32 s100, s22, s26
	s_cmp_lt_i32 s100, 1
	s_cbranch_scc1 .Lmg4_done
	s_min_i32 s100, s100, 8
	s_sub_i32 s101, 8, s100
	s_lshl_b32 s7, s101, 5
	s_sub_i32 s28, s6, s7
	s_ashr_i32 s29, s28, 31
	s_lshl_b64 s[28:29], s[28:29], 1
	v_lshl_add_u64 v[212:213], v[22:23], 0, s[28:29]
	v_lshl_add_u64 v[228:229], v[24:25], 0, s[28:29]
	v_lshl_add_u64 v[238:239], v[10:11], 0, s[28:29]
	s_add_i32 s26, s26, s100
	s_lshl_b32 s7, s100, 5
	s_add_i32 s6, s6, s7
	s_cmp_eq_u32 s101, 0
	s_cbranch_scc1 .Lmg4_L0
	s_cmp_eq_u32 s101, 1
	s_cbranch_scc1 .Lmg4_L1
	s_cmp_eq_u32 s101, 2
	s_cbranch_scc1 .Lmg4_L2
	s_cmp_eq_u32 s101, 3
	s_cbranch_scc1 .Lmg4_L3
	s_cmp_eq_u32 s101, 4
	s_cbranch_scc1 .Lmg4_L4
	s_cmp_eq_u32 s101, 5
	s_cbranch_scc1 .Lmg4_L5
	s_cmp_eq_u32 s101, 6
	s_cbranch_scc1 .Lmg4_L6
	s_branch .Lmg4_L7

.Lmg4_L7:
	global_load_dwordx4 v[30:33], v[212:213], off offset:448
	global_load_dwordx4 v[34:37], v[228:229], off offset:448
	global_load_dwordx4 v[38:41], v[238:239], off offset:448
	s_cmp_eq_u32 s101, 0
	s_cbranch_scc1 .Lmg4_M0
	s_cmp_eq_u32 s101, 1
	s_cbranch_scc1 .Lmg4_M1
	s_cmp_eq_u32 s101, 2
	s_cbranch_scc1 .Lmg4_M2
	s_cmp_eq_u32 s101, 3
	s_cbranch_scc1 .Lmg4_M3
	s_cmp_eq_u32 s101, 4
	s_cbranch_scc1 .Lmg4_M4
	s_cmp_eq_u32 s101, 5
	s_cbranch_scc1 .Lmg4_M5
	s_cmp_eq_u32 s101, 6
	s_cbranch_scc1 .Lmg4_M6
	s_branch .Lmg4_M7

.Lmg4_M7:
	s_waitcnt vmcnt(0)
	v_mfma_f32_16x16x32_bf16 v[6:9], v[34:37], v[38:41], v[6:9]
	v_mfma_f32_16x16x32_bf16 v[2:5], v[30:33], v[38:41], v[2:5]
	s_branch .Lmg4_top
.Lmg4_done:
.LBB0_950:
	s_andn2_b64 vcc, exec, s[8:9]
	s_nop 5
	ds_write_b128 v28, v[2:5]
	ds_write_b128 v28, v[6:9] offset:1024
	s_waitcnt vmcnt(0) lgkmcnt(0)
	s_barrier
	s_cbranch_vccnz .LBB0_946
	ds_read_b128 v[2:5], v29
	s_waitcnt lgkmcnt(0)
	v_pk_add_f32 v[6:7], v[4:5], 0 op_sel_hi:[1,0]
	v_pk_add_f32 v[8:9], v[2:3], 0 op_sel_hi:[1,0]
	ds_read_b128 v[2:5], v29 offset:1024
	s_waitcnt lgkmcnt(0)
	v_pk_add_f32 v[22:23], v[4:5], 0 op_sel_hi:[1,0]
	v_pk_add_f32 v[24:25], v[2:3], 0 op_sel_hi:[1,0]
	ds_read_b128 v[2:5], v29 offset:2048
	s_waitcnt lgkmcnt(0)
	v_pk_add_f32 v[6:7], v[6:7], v[4:5]
	v_pk_add_f32 v[8:9], v[8:9], v[2:3]
	ds_read_b128 v[2:5], v29 offset:3072
	s_waitcnt lgkmcnt(0)
	v_pk_add_f32 v[22:23], v[22:23], v[4:5]
	v_pk_add_f32 v[24:25], v[24:25], v[2:3]
	ds_read_b128 v[2:5], v29 offset:4096
	s_waitcnt lgkmcnt(0)
	v_pk_add_f32 v[6:7], v[6:7], v[4:5]
	v_pk_add_f32 v[8:9], v[8:9], v[2:3]
	ds_read_b128 v[2:5], v29 offset:5120
	s_waitcnt lgkmcnt(0)
	v_pk_add_f32 v[22:23], v[22:23], v[4:5]
	v_pk_add_f32 v[24:25], v[24:25], v[2:3]
	ds_read_b128 v[2:5], v29 offset:6144
	s_waitcnt lgkmcnt(0)
	v_pk_add_f32 v[6:7], v[6:7], v[4:5]
	v_pk_add_f32 v[8:9], v[8:9], v[2:3]
	ds_read_b128 v[2:5], v29 offset:7168
	s_waitcnt lgkmcnt(0)
	v_pk_add_f32 v[22:23], v[22:23], v[4:5]
	v_pk_add_f32 v[24:25], v[24:25], v[2:3]
	ds_read_b128 v[2:5], v29 offset:8192
	s_waitcnt lgkmcnt(0)
	v_pk_add_f32 v[6:7], v[6:7], v[4:5]
	v_pk_add_f32 v[8:9], v[8:9], v[2:3]
	ds_read_b128 v[2:5], v29 offset:9216
	s_waitcnt lgkmcnt(0)
	v_pk_add_f32 v[22:23], v[22:23], v[4:5]
	v_pk_add_f32 v[24:25], v[24:25], v[2:3]
	ds_read_b128 v[2:5], v29 offset:10240
	s_waitcnt lgkmcnt(0)
	v_pk_add_f32 v[6:7], v[6:7], v[4:5]
	v_pk_add_f32 v[8:9], v[8:9], v[2:3]
	ds_read_b128 v[2:5], v29 offset:11264
	s_waitcnt lgkmcnt(0)
	v_pk_add_f32 v[22:23], v[22:23], v[4:5]
	v_pk_add_f32 v[24:25], v[24:25], v[2:3]
	ds_read_b128 v[2:5], v29 offset:12288
	s_waitcnt lgkmcnt(0)
	v_pk_add_f32 v[6:7], v[6:7], v[4:5]
	v_pk_add_f32 v[8:9], v[8:9], v[2:3]
	ds_read_b128 v[2:5], v29 offset:13312
	s_waitcnt lgkmcnt(0)
	v_pk_add_f32 v[22:23], v[22:23], v[4:5]
	v_pk_add_f32 v[24:25], v[24:25], v[2:3]
	ds_read_b128 v[2:5], v29 offset:14336
	s_waitcnt lgkmcnt(0)
	v_pk_add_f32 v[6:7], v[6:7], v[4:5]
	v_pk_add_f32 v[8:9], v[8:9], v[2:3]
	ds_read_b128 v[2:5], v29 offset:15360
	s_waitcnt lgkmcnt(0)
	v_pk_add_f32 v[22:23], v[22:23], v[4:5]
	v_pk_add_f32 v[4:5], v[24:25], v[2:3]
	v_or_b32_e32 v24, s23, v26
	v_ashrrev_i32_e32 v25, 31, v24
	v_cvt_pk_bf16_f32 v3, v6, v7
	v_lshlrev_b64 v[6:7], 1, v[24:25]
	v_cvt_pk_bf16_f32 v2, v8, v9
	v_cvt_pk_bf16_f32 v4, v4, v5
	v_cvt_pk_bf16_f32 v5, v22, v23
	v_lshl_add_u64 v[8:9], v[14:15], 0, v[6:7]
	global_store_dwordx4 v[8:9], v[2:5], off
	v_lshl_add_u64 v[8:9], v[16:17], 0, v[6:7]
	global_store_dwordx4 v[8:9], v[2:5], off
	v_lshl_add_u64 v[8:9], v[18:19], 0, v[6:7]
	v_lshl_add_u64 v[6:7], v[20:21], 0, v[6:7]
	global_store_dwordx4 v[8:9], v[2:5], off
	global_store_dwordx4 v[6:7], v[2:5], off
	s_branch .LBB0_946

.Lmg5_done:
.LBB0_1265:
	s_lshl_b32 s0, s7, 11
	v_and_b32_e32 v20, 63, v20
	s_add_i32 s0, s0, 0
	v_lshl_add_u32 v0, v20, 4, s0
	s_cmp_gt_u32 s6, 63
	s_nop 1
	ds_write_b128 v0, v[2:5]
	ds_write_b128 v0, v[6:9] offset:1024
	s_waitcnt lgkmcnt(0)
	s_barrier
	s_cbranch_scc1 .LBB0_1291
	v_lshlrev_b32_e32 v0, 2, v20
	v_lshl_add_u32 v0, v0, 2, 0
	ds_read_b128 v[2:5], v0
	v_readlane_b32 s0, v254, 37
	s_movk_i32 s70, 0x80
	v_cmp_gt_u32_e32 vcc, 16, v20
	s_waitcnt lgkmcnt(0)
	v_pk_add_f32 v[6:7], v[4:5], 0 op_sel_hi:[1,0]
	v_pk_add_f32 v[8:9], v[2:3], 0 op_sel_hi:[1,0]
	ds_read_b128 v[2:5], v0 offset:1024
	s_waitcnt lgkmcnt(0)
	v_pk_add_f32 v[10:11], v[4:5], 0 op_sel_hi:[1,0]
	v_pk_add_f32 v[12:13], v[2:3], 0 op_sel_hi:[1,0]
	ds_read_b128 v[2:5], v0 offset:2048
	s_waitcnt lgkmcnt(0)
	v_pk_add_f32 v[6:7], v[6:7], v[4:5]
	v_pk_add_f32 v[8:9], v[8:9], v[2:3]
	ds_read_b128 v[2:5], v0 offset:3072
	s_waitcnt lgkmcnt(0)
	v_pk_add_f32 v[10:11], v[10:11], v[4:5]
	v_pk_add_f32 v[12:13], v[12:13], v[2:3]
	ds_read_b128 v[2:5], v0 offset:4096
	s_waitcnt lgkmcnt(0)
	v_pk_add_f32 v[6:7], v[6:7], v[4:5]
	v_pk_add_f32 v[8:9], v[8:9], v[2:3]
	ds_read_b128 v[2:5], v0 offset:5120
	s_waitcnt lgkmcnt(0)
	v_pk_add_f32 v[10:11], v[10:11], v[4:5]
	v_pk_add_f32 v[12:13], v[12:13], v[2:3]
	ds_read_b128 v[2:5], v0 offset:6144
	s_waitcnt lgkmcnt(0)
	v_pk_add_f32 v[6:7], v[6:7], v[4:5]
	v_pk_add_f32 v[8:9], v[8:9], v[2:3]
	ds_read_b128 v[2:5], v0 offset:7168
	s_waitcnt lgkmcnt(0)
	v_pk_add_f32 v[10:11], v[10:11], v[4:5]
	v_pk_add_f32 v[12:13], v[12:13], v[2:3]
	ds_read_b128 v[2:5], v0 offset:8192
	s_waitcnt lgkmcnt(0)
	v_pk_add_f32 v[6:7], v[6:7], v[4:5]
	v_pk_add_f32 v[8:9], v[8:9], v[2:3]
	ds_read_b128 v[2:5], v0 offset:9216
	s_waitcnt lgkmcnt(0)
	v_pk_add_f32 v[10:11], v[10:11], v[4:5]
	v_pk_add_f32 v[12:13], v[12:13], v[2:3]
	ds_read_b128 v[2:5], v0 offset:10240
	s_waitcnt lgkmcnt(0)
	v_pk_add_f32 v[6:7], v[6:7], v[4:5]
	v_pk_add_f32 v[8:9], v[8:9], v[2:3]
	ds_read_b128 v[2:5], v0 offset:11264
	s_waitcnt lgkmcnt(0)
	v_pk_add_f32 v[10:11], v[10:11], v[4:5]
	v_pk_add_f32 v[12:13], v[12:13], v[2:3]
	ds_read_b128 v[2:5], v0 offset:12288
	s_waitcnt lgkmcnt(0)
	v_pk_add_f32 v[14:15], v[6:7], v[4:5]
	v_pk_add_f32 v[8:9], v[8:9], v[2:3]
	ds_read_b128 v[2:5], v0 offset:13312
	s_waitcnt lgkmcnt(0)
	v_pk_add_f32 v[10:11], v[10:11], v[4:5]
	ds_read_b128 v[4:7], v0 offset:14336
	v_pk_add_f32 v[22:23], v[12:13], v[2:3]
	s_waitcnt lgkmcnt(0)
	v_pk_add_f32 v[2:3], v[14:15], v[6:7]
	v_pk_add_f32 v[4:5], v[8:9], v[4:5]
	ds_read_b128 v[6:9], v0 offset:15360
	v_or_b32_e32 v14, s0, v17
	v_lshlrev_b32_e32 v0, 13, v16
	v_ashrrev_i32_e32 v15, 31, v14
	s_mov_b32 s0, 0x3fb504f3
	s_waitcnt lgkmcnt(0)
	v_pk_add_f32 v[12:13], v[10:11], v[8:9]
	v_pk_add_f32 v[10:11], v[22:23], v[6:7]
	v_lshl_add_u64 v[6:7], s[28:29], 0, v[0:1]
	v_lshl_add_u64 v[16:17], v[14:15], 2, v[6:7]
	global_load_dwordx4 v[22:25], v[16:17], off offset:16
	global_load_dwordx4 v[6:9], v[16:17], off
	s_waitcnt vmcnt(0)
	v_pk_fma_f32 v[8:9], v[8:9], s[0:1], v[2:3] op_sel_hi:[1,0,1]
	v_pk_fma_f32 v[6:7], v[6:7], s[0:1], v[4:5] op_sel_hi:[1,0,1]
	v_pk_fma_f32 v[2:3], v[24:25], s[0:1], v[12:13] op_sel_hi:[1,0,1]
	v_pk_fma_f32 v[4:5], v[22:23], s[0:1], v[10:11] op_sel_hi:[1,0,1]
	v_pk_mov_b32 v[10:11], v[6:7], v[8:9] op_sel:[1,0]
	v_mov_b32_e32 v12, v6
	v_mov_b32_e32 v13, v9
	v_pk_add_f32 v[10:11], v[10:11], v[12:13]
	v_pk_mul_f32 v[12:13], v[8:9], v[8:9]
	v_pk_mul_f32 v[22:23], v[6:7], v[6:7]
	v_mul_f32_e32 v0, v4, v4
	v_pk_mov_b32 v[24:25], v[22:23], v[12:13] op_sel:[1,0]
	v_mov_b32_e32 v23, v13
	v_pk_add_f32 v[12:13], v[24:25], v[22:23]
	v_pk_fma_f32 v[22:23], v[4:5], v[4:5], v[0:1] op_sel_hi:[1,1,0]
	v_pk_add_f32 v[12:13], v[12:13], v[12:13] op_sel_hi:[0,1]
	v_mov_b32_e32 v12, v148
	v_mov_b32_e32 v22, v3
	v_lshlrev_b32_e32 v12, 2, v12
	v_bitop3_b32 v21, v12, 64, v232 bitop3:0x6c
	v_mov_b32_e32 v12, v148
	v_mul_f32_e32 v0, v2, v2
	v_lshlrev_b32_e32 v12, 2, v12
	v_bitop3_b32 v26, v12, 64, v232 bitop3:0x6c
	v_mov_b32_e32 v12, v2
	v_pk_add_f32 v[12:13], v[12:13], v[22:23]
	v_pk_add_f32 v[22:23], v[4:5], v[4:5] op_sel:[0,1] op_sel_hi:[1,0]
	v_pk_mul_f32 v[24:25], v[2:3], v[2:3]
	v_pk_add_f32 v[10:11], v[10:11], v[10:11] op_sel:[0,1] op_sel_hi:[1,0]
	v_mov_b32_e32 v23, v25
	v_mov_b32_e32 v11, v0
	v_pk_add_f32 v[10:11], v[10:11], v[22:23]
	v_mov_b32_e32 v0, v148
	v_pk_add_f32 v[10:11], v[10:11], v[12:13]
	ds_bpermute_b32 v12, v21, v10
	ds_bpermute_b32 v13, v26, v11
	s_movk_i32 s0, 0x80
	v_lshlrev_b32_e32 v0, 2, v0
	v_bitop3_b32 v0, v0, s0, v232 bitop3:0x6c
	s_waitcnt lgkmcnt(0)
	v_pk_add_f32 v[10:11], v[10:11], v[12:13]
	ds_bpermute_b32 v12, v0, v10
	v_mov_b32_e32 v0, v148
	s_nop 0
	v_lshlrev_b32_e32 v0, 2, v0
	v_bitop3_b32 v0, v0, s0, v232 bitop3:0x6c
	ds_bpermute_b32 v13, v0, v11
	s_and_saveexec_b64 s[0:1], vcc
	s_cbranch_execz .LBB0_1268
	v_readlane_b32 s6, v254, 37
	s_waitcnt lgkmcnt(0)
	v_pk_add_f32 v[10:11], v[10:11], v[12:13]
	v_or_b32_e32 v12, s6, v19
	v_readlane_b32 s6, v254, 42
	v_ashrrev_i32_e32 v13, 31, v12
	v_readlane_b32 s7, v254, 43
	s_nop 1
	v_lshl_add_u64 v[12:13], v[12:13], 2, s[6:7]
	global_store_dwordx2 v[12:13], v[10:11], off sc1
